# P4 work queues: only wave 0 of each workgroup probes the other XCD queues after its own is empty
# speedup vs baseline: 1.0132x; 1.0014x over previous
.LBB0_519:
	v_readfirstlane_b32 s98, v210
	s_cmp_lg_u32 s98, 0
	s_cbranch_scc1 .LBB0_592
	s_add_i32 s18, s18, 1
	s_add_i32 s8, s8, 1
	s_xor_b64 s[58:59], s[58:59], -1
	s_cmp_eq_u32 s18, 8
	s_cbranch_scc1 .LBB0_592
